# kv-projection epilogue: the 8 row-statistics loads issued together with counted waits instead of 8 dependent load-wait-store round trips
# speedup vs baseline: 1.0688x; 1.0043x over previous
.LBB0_771:
	v_lshl_add_u32 v142, s0, 8, v144
	v_ashrrev_i32_e32 v143, 31, v142
	v_lshl_add_u64 v[148:149], v[142:143], 4, s[8:9]
	global_load_dwordx4 v[148:151], v[148:149], off
	v_or_b32_e32 v174, 16, v142
	v_ashrrev_i32_e32 v175, 31, v174
	v_lshl_add_u64 v[156:157], v[174:175], 4, s[8:9]
	global_load_dwordx4 v[156:159], v[156:157], off
	v_or_b32_e32 v174, 32, v142
	v_ashrrev_i32_e32 v175, 31, v174
	v_lshl_add_u64 v[160:161], v[174:175], 4, s[8:9]
	global_load_dwordx4 v[160:163], v[160:161], off
	v_or_b32_e32 v174, 48, v142
	v_ashrrev_i32_e32 v175, 31, v174
	v_lshl_add_u64 v[164:165], v[174:175], 4, s[8:9]
	global_load_dwordx4 v[164:167], v[164:165], off
	v_add_u32_e32 v174, 128, v142
	v_ashrrev_i32_e32 v175, 31, v174
	v_lshl_add_u64 v[176:177], v[174:175], 4, s[8:9]
	global_load_dwordx4 v[176:179], v[176:177], off
	v_add_u32_e32 v174, 144, v142
	v_ashrrev_i32_e32 v175, 31, v174
	v_lshl_add_u64 v[180:181], v[174:175], 4, s[8:9]
	global_load_dwordx4 v[180:183], v[180:181], off
	v_add_u32_e32 v174, 160, v142
	v_ashrrev_i32_e32 v175, 31, v174
	v_lshl_add_u64 v[184:185], v[174:175], 4, s[8:9]
	global_load_dwordx4 v[184:187], v[184:185], off
	v_add_u32_e32 v174, 176, v142
	v_ashrrev_i32_e32 v175, 31, v174
	v_lshl_add_u64 v[188:189], v[174:175], 4, s[8:9]
	global_load_dwordx4 v[188:191], v[188:189], off
	s_lshl_b32 s0, s1, 8
	s_or_b32 s0, s0, s33
	s_ashr_i32 s0, s0, 6
	s_ashr_i32 s1, s0, 31
	s_lshl_b64 s[20:21], s[0:1], 16
	s_or_b32 s0, s0, 2
	s_ashr_i32 s1, s0, 31
	s_lshl_b64 s[22:23], s[0:1], 16
	s_mov_b64 s[0:1], -1
	s_andn2_b64 vcc, exec, s[4:5]
	s_waitcnt vmcnt(7)
	v_mov_b32_e32 v152, v149
	v_mov_b32_e32 v153, v150
	v_mov_b32_e32 v149, v151
	v_pk_add_f32 v[148:149], v[152:153], v[148:149]
	s_nop 0
	v_add_f32_e32 v147, v148, v149
	v_fmamk_f32 v147, v147, 0x3a800000, v207
	v_rsq_f32_e32 v148, v147
	s_nop 0
	v_pk_mul_f32 v[126:127], v[126:127], v[148:149] op_sel_hi:[1,0]
	v_pk_mul_f32 v[150:151], v[124:125], v[148:149] op_sel_hi:[1,0]
	v_pk_mul_f32 v[124:125], v[122:123], v[148:149] op_sel_hi:[1,0]
	v_cvt_pk_bf16_f32 v122, v126, v127
	v_lshl_add_u64 v[126:127], s[20:21], 0, v[142:143]
	v_lshlrev_b64 v[126:127], 7, v[126:127]
	v_pk_mul_f32 v[128:129], v[128:129], v[148:149] op_sel_hi:[1,0]
	v_lshl_add_u64 v[126:127], v[136:137], 0, v[126:127]
	v_cvt_pk_bf16_f32 v123, v128, v129
	v_pk_mul_f32 v[118:119], v[118:119], v[148:149] op_sel_hi:[1,0]
	v_cvt_pk_bf16_f32 v124, v124, v125
	v_cvt_pk_bf16_f32 v125, v150, v151
	global_store_dwordx4 v[126:127], v[122:125], off
	v_pk_mul_f32 v[120:121], v[120:121], v[148:149] op_sel_hi:[1,0]
	s_nop 0
	v_pk_mul_f32 v[122:123], v[116:117], v[148:149] op_sel_hi:[1,0]
	v_pk_mul_f32 v[116:117], v[114:115], v[148:149] op_sel_hi:[1,0]
	v_cvt_pk_bf16_f32 v114, v118, v119
	v_lshl_add_u64 v[118:119], s[22:23], 0, v[142:143]
	v_lshlrev_b64 v[118:119], 7, v[118:119]
	v_lshl_add_u64 v[118:119], v[136:137], 0, v[118:119]
	v_cvt_pk_bf16_f32 v115, v120, v121
	v_cvt_pk_bf16_f32 v116, v116, v117
	v_cvt_pk_bf16_f32 v117, v122, v123
	global_store_dwordx4 v[118:119], v[114:117], off
	v_or_b32_e32 v118, 16, v142
	v_ashrrev_i32_e32 v119, 31, v118
	s_waitcnt vmcnt(8)
	v_mov_b32_e32 v114, v156
	v_mov_b32_e32 v115, v157
	v_mov_b32_e32 v116, v158
	v_mov_b32_e32 v117, v159
	v_mov_b32_e32 v120, v115
	v_mov_b32_e32 v121, v116
	v_mov_b32_e32 v115, v117
	v_pk_add_f32 v[114:115], v[120:121], v[114:115]
	s_nop 0
	v_add_f32_e32 v114, v114, v115
	v_fmamk_f32 v114, v114, 0x3a800000, v207
	v_rsq_f32_e32 v114, v114
	s_nop 0
	v_pk_mul_f32 v[110:111], v[110:111], v[114:115] op_sel_hi:[1,0]
	v_pk_mul_f32 v[116:117], v[108:109], v[114:115] op_sel_hi:[1,0]
	v_pk_mul_f32 v[108:109], v[106:107], v[114:115] op_sel_hi:[1,0]
	v_cvt_pk_bf16_f32 v106, v110, v111
	v_lshl_add_u64 v[110:111], s[20:21], 0, v[118:119]
	v_lshlrev_b64 v[110:111], 7, v[110:111]
	v_pk_mul_f32 v[112:113], v[112:113], v[114:115] op_sel_hi:[1,0]
	v_lshl_add_u64 v[110:111], v[136:137], 0, v[110:111]
	v_cvt_pk_bf16_f32 v107, v112, v113
	v_pk_mul_f32 v[102:103], v[102:103], v[114:115] op_sel_hi:[1,0]
	v_cvt_pk_bf16_f32 v108, v108, v109
	v_cvt_pk_bf16_f32 v109, v116, v117
	global_store_dwordx4 v[110:111], v[106:109], off
	v_pk_mul_f32 v[104:105], v[104:105], v[114:115] op_sel_hi:[1,0]
	s_nop 0
	v_pk_mul_f32 v[106:107], v[100:101], v[114:115] op_sel_hi:[1,0]
	v_pk_mul_f32 v[100:101], v[98:99], v[114:115] op_sel_hi:[1,0]
	v_cvt_pk_bf16_f32 v98, v102, v103
	v_lshl_add_u64 v[102:103], s[22:23], 0, v[118:119]
	v_lshlrev_b64 v[102:103], 7, v[102:103]
	v_lshl_add_u64 v[102:103], v[136:137], 0, v[102:103]
	v_cvt_pk_bf16_f32 v99, v104, v105
	v_cvt_pk_bf16_f32 v100, v100, v101
	v_cvt_pk_bf16_f32 v101, v106, v107
	global_store_dwordx4 v[102:103], v[98:101], off
	v_or_b32_e32 v102, 32, v142
	v_ashrrev_i32_e32 v103, 31, v102
	s_waitcnt vmcnt(9)
	v_mov_b32_e32 v98, v160
	v_mov_b32_e32 v99, v161
	v_mov_b32_e32 v100, v162
	v_mov_b32_e32 v101, v163
	v_mov_b32_e32 v104, v99
	v_mov_b32_e32 v105, v100
	v_mov_b32_e32 v99, v101
	v_pk_add_f32 v[98:99], v[104:105], v[98:99]
	s_nop 0
	v_add_f32_e32 v98, v98, v99
	v_fmamk_f32 v98, v98, 0x3a800000, v207
	v_rsq_f32_e32 v98, v98
	s_nop 0
	v_pk_mul_f32 v[92:93], v[92:93], v[98:99] op_sel_hi:[1,0]
	v_pk_mul_f32 v[100:101], v[90:91], v[98:99] op_sel_hi:[1,0]
	v_pk_mul_f32 v[90:91], v[88:89], v[98:99] op_sel_hi:[1,0]
	v_cvt_pk_bf16_f32 v88, v92, v93
	v_lshl_add_u64 v[92:93], s[20:21], 0, v[102:103]
	v_lshlrev_b64 v[92:93], 7, v[92:93]
	v_pk_mul_f32 v[94:95], v[94:95], v[98:99] op_sel_hi:[1,0]
	v_lshl_add_u64 v[92:93], v[136:137], 0, v[92:93]
	v_cvt_pk_bf16_f32 v89, v94, v95
	v_pk_mul_f32 v[84:85], v[84:85], v[98:99] op_sel_hi:[1,0]
	v_cvt_pk_bf16_f32 v90, v90, v91
	v_cvt_pk_bf16_f32 v91, v100, v101
	global_store_dwordx4 v[92:93], v[88:91], off
	v_pk_mul_f32 v[86:87], v[86:87], v[98:99] op_sel_hi:[1,0]
	s_nop 0
	v_pk_mul_f32 v[88:89], v[82:83], v[98:99] op_sel_hi:[1,0]
	v_pk_mul_f32 v[82:83], v[80:81], v[98:99] op_sel_hi:[1,0]
	v_cvt_pk_bf16_f32 v80, v84, v85
	v_lshl_add_u64 v[84:85], s[22:23], 0, v[102:103]
	v_lshlrev_b64 v[84:85], 7, v[84:85]
	v_lshl_add_u64 v[84:85], v[136:137], 0, v[84:85]
	v_cvt_pk_bf16_f32 v81, v86, v87
	v_cvt_pk_bf16_f32 v82, v82, v83
	v_cvt_pk_bf16_f32 v83, v88, v89
	global_store_dwordx4 v[84:85], v[80:83], off
	v_or_b32_e32 v84, 48, v142
	v_ashrrev_i32_e32 v85, 31, v84
	s_waitcnt vmcnt(10)
	v_mov_b32_e32 v80, v164
	v_mov_b32_e32 v81, v165
	v_mov_b32_e32 v82, v166
	v_mov_b32_e32 v83, v167
	v_mov_b32_e32 v86, v81
	v_mov_b32_e32 v87, v82
	v_mov_b32_e32 v81, v83
	v_pk_add_f32 v[80:81], v[86:87], v[80:81]
	s_nop 0
	v_add_f32_e32 v80, v80, v81
	v_fmamk_f32 v80, v80, 0x3a800000, v207
	v_rsq_f32_e32 v80, v80
	s_nop 0
	v_pk_mul_f32 v[76:77], v[76:77], v[80:81] op_sel_hi:[1,0]
	v_pk_mul_f32 v[82:83], v[74:75], v[80:81] op_sel_hi:[1,0]
	v_pk_mul_f32 v[74:75], v[72:73], v[80:81] op_sel_hi:[1,0]
	v_cvt_pk_bf16_f32 v72, v76, v77
	v_lshl_add_u64 v[76:77], s[20:21], 0, v[84:85]
	v_lshlrev_b64 v[76:77], 7, v[76:77]
	v_pk_mul_f32 v[78:79], v[78:79], v[80:81] op_sel_hi:[1,0]
	v_lshl_add_u64 v[76:77], v[136:137], 0, v[76:77]
	v_cvt_pk_bf16_f32 v73, v78, v79
	v_pk_mul_f32 v[68:69], v[68:69], v[80:81] op_sel_hi:[1,0]
	v_cvt_pk_bf16_f32 v74, v74, v75
	v_cvt_pk_bf16_f32 v75, v82, v83
	global_store_dwordx4 v[76:77], v[72:75], off
	v_pk_mul_f32 v[70:71], v[70:71], v[80:81] op_sel_hi:[1,0]
	s_nop 0
	v_pk_mul_f32 v[72:73], v[66:67], v[80:81] op_sel_hi:[1,0]
	v_pk_mul_f32 v[66:67], v[64:65], v[80:81] op_sel_hi:[1,0]
	v_cvt_pk_bf16_f32 v64, v68, v69
	v_lshl_add_u64 v[68:69], s[22:23], 0, v[84:85]
	v_lshlrev_b64 v[68:69], 7, v[68:69]
	v_lshl_add_u64 v[68:69], v[136:137], 0, v[68:69]
	v_cvt_pk_bf16_f32 v65, v70, v71
	v_cvt_pk_bf16_f32 v66, v66, v67
	v_cvt_pk_bf16_f32 v67, v72, v73
	global_store_dwordx4 v[68:69], v[64:67], off
	v_add_u32_e32 v68, 0x80, v142
	v_ashrrev_i32_e32 v69, 31, v68
	s_waitcnt vmcnt(11)
	v_mov_b32_e32 v64, v176
	v_mov_b32_e32 v65, v177
	v_mov_b32_e32 v66, v178
	v_mov_b32_e32 v67, v179
	v_mov_b32_e32 v70, v65
	v_mov_b32_e32 v71, v66
	v_mov_b32_e32 v65, v67
	v_pk_add_f32 v[64:65], v[70:71], v[64:65]
	s_nop 0
	v_add_f32_e32 v64, v64, v65
	v_fmamk_f32 v64, v64, 0x3a800000, v207
	v_rsq_f32_e32 v64, v64
	s_nop 0
	v_pk_mul_f32 v[60:61], v[60:61], v[64:65] op_sel_hi:[1,0]
	v_pk_mul_f32 v[66:67], v[58:59], v[64:65] op_sel_hi:[1,0]
	v_pk_mul_f32 v[58:59], v[56:57], v[64:65] op_sel_hi:[1,0]
	v_cvt_pk_bf16_f32 v56, v60, v61
	v_lshl_add_u64 v[60:61], s[20:21], 0, v[68:69]
	v_lshlrev_b64 v[60:61], 7, v[60:61]
	v_pk_mul_f32 v[62:63], v[62:63], v[64:65] op_sel_hi:[1,0]
	v_lshl_add_u64 v[60:61], v[136:137], 0, v[60:61]
	v_cvt_pk_bf16_f32 v57, v62, v63
	v_pk_mul_f32 v[52:53], v[52:53], v[64:65] op_sel_hi:[1,0]
	v_cvt_pk_bf16_f32 v58, v58, v59
	v_cvt_pk_bf16_f32 v59, v66, v67
	global_store_dwordx4 v[60:61], v[56:59], off
	v_pk_mul_f32 v[54:55], v[54:55], v[64:65] op_sel_hi:[1,0]
	s_nop 0
	v_pk_mul_f32 v[56:57], v[50:51], v[64:65] op_sel_hi:[1,0]
	v_pk_mul_f32 v[50:51], v[48:49], v[64:65] op_sel_hi:[1,0]
	v_cvt_pk_bf16_f32 v48, v52, v53
	v_lshl_add_u64 v[52:53], s[22:23], 0, v[68:69]
	v_lshlrev_b64 v[52:53], 7, v[52:53]
	v_lshl_add_u64 v[52:53], v[136:137], 0, v[52:53]
	v_cvt_pk_bf16_f32 v49, v54, v55
	v_cvt_pk_bf16_f32 v50, v50, v51
	v_cvt_pk_bf16_f32 v51, v56, v57
	global_store_dwordx4 v[52:53], v[48:51], off
	v_add_u32_e32 v52, 0x90, v142
	v_ashrrev_i32_e32 v53, 31, v52
	s_waitcnt vmcnt(12)
	v_mov_b32_e32 v48, v180
	v_mov_b32_e32 v49, v181
	v_mov_b32_e32 v50, v182
	v_mov_b32_e32 v51, v183
	v_mov_b32_e32 v54, v49
	v_mov_b32_e32 v55, v50
	v_mov_b32_e32 v49, v51
	v_pk_add_f32 v[48:49], v[54:55], v[48:49]
	s_nop 0
	v_add_f32_e32 v48, v48, v49
	v_fmamk_f32 v48, v48, 0x3a800000, v207
	v_rsq_f32_e32 v48, v48
	s_nop 0
	v_pk_mul_f32 v[44:45], v[44:45], v[48:49] op_sel_hi:[1,0]
	v_pk_mul_f32 v[50:51], v[42:43], v[48:49] op_sel_hi:[1,0]
	v_pk_mul_f32 v[42:43], v[40:41], v[48:49] op_sel_hi:[1,0]
	v_cvt_pk_bf16_f32 v40, v44, v45
	v_lshl_add_u64 v[44:45], s[20:21], 0, v[52:53]
	v_lshlrev_b64 v[44:45], 7, v[44:45]
	v_pk_mul_f32 v[46:47], v[46:47], v[48:49] op_sel_hi:[1,0]
	v_lshl_add_u64 v[44:45], v[136:137], 0, v[44:45]
	v_cvt_pk_bf16_f32 v41, v46, v47
	v_pk_mul_f32 v[36:37], v[36:37], v[48:49] op_sel_hi:[1,0]
	v_cvt_pk_bf16_f32 v42, v42, v43
	v_cvt_pk_bf16_f32 v43, v50, v51
	global_store_dwordx4 v[44:45], v[40:43], off
	v_pk_mul_f32 v[38:39], v[38:39], v[48:49] op_sel_hi:[1,0]
	s_nop 0
	v_pk_mul_f32 v[40:41], v[34:35], v[48:49] op_sel_hi:[1,0]
	v_pk_mul_f32 v[34:35], v[32:33], v[48:49] op_sel_hi:[1,0]
	v_cvt_pk_bf16_f32 v32, v36, v37
	v_lshl_add_u64 v[36:37], s[22:23], 0, v[52:53]
	v_lshlrev_b64 v[36:37], 7, v[36:37]
	v_lshl_add_u64 v[36:37], v[136:137], 0, v[36:37]
	v_cvt_pk_bf16_f32 v33, v38, v39
	v_cvt_pk_bf16_f32 v34, v34, v35
	v_cvt_pk_bf16_f32 v35, v40, v41
	global_store_dwordx4 v[36:37], v[32:35], off
	v_add_u32_e32 v36, 0xa0, v142
	v_ashrrev_i32_e32 v37, 31, v36
	s_waitcnt vmcnt(13)
	v_mov_b32_e32 v32, v184
	v_mov_b32_e32 v33, v185
	v_mov_b32_e32 v34, v186
	v_mov_b32_e32 v35, v187
	v_mov_b32_e32 v38, v33
	v_mov_b32_e32 v39, v34
	v_mov_b32_e32 v33, v35
	v_pk_add_f32 v[32:33], v[38:39], v[32:33]
	s_nop 0
	v_add_f32_e32 v32, v32, v33
	v_fmamk_f32 v32, v32, 0x3a800000, v207
	v_rsq_f32_e32 v32, v32
	s_nop 0
	v_pk_mul_f32 v[28:29], v[28:29], v[32:33] op_sel_hi:[1,0]
	v_pk_mul_f32 v[34:35], v[26:27], v[32:33] op_sel_hi:[1,0]
	v_pk_mul_f32 v[26:27], v[24:25], v[32:33] op_sel_hi:[1,0]
	v_cvt_pk_bf16_f32 v24, v28, v29
	v_lshl_add_u64 v[28:29], s[20:21], 0, v[36:37]
	v_lshlrev_b64 v[28:29], 7, v[28:29]
	v_pk_mul_f32 v[30:31], v[30:31], v[32:33] op_sel_hi:[1,0]
	v_lshl_add_u64 v[28:29], v[136:137], 0, v[28:29]
	v_cvt_pk_bf16_f32 v25, v30, v31
	v_pk_mul_f32 v[20:21], v[20:21], v[32:33] op_sel_hi:[1,0]
	v_cvt_pk_bf16_f32 v26, v26, v27
	v_cvt_pk_bf16_f32 v27, v34, v35
	global_store_dwordx4 v[28:29], v[24:27], off
	v_pk_mul_f32 v[22:23], v[22:23], v[32:33] op_sel_hi:[1,0]
	s_nop 0
	v_pk_mul_f32 v[24:25], v[18:19], v[32:33] op_sel_hi:[1,0]
	v_pk_mul_f32 v[18:19], v[16:17], v[32:33] op_sel_hi:[1,0]
	v_cvt_pk_bf16_f32 v16, v20, v21
	v_lshl_add_u64 v[20:21], s[22:23], 0, v[36:37]
	v_lshlrev_b64 v[20:21], 7, v[20:21]
	v_lshl_add_u64 v[20:21], v[136:137], 0, v[20:21]
	v_cvt_pk_bf16_f32 v17, v22, v23
	v_cvt_pk_bf16_f32 v18, v18, v19
	v_cvt_pk_bf16_f32 v19, v24, v25
	global_store_dwordx4 v[20:21], v[16:19], off
	v_add_u32_e32 v20, 0xb0, v142
	v_ashrrev_i32_e32 v21, 31, v20
	s_waitcnt vmcnt(14)
	v_mov_b32_e32 v16, v188
	v_mov_b32_e32 v17, v189
	v_mov_b32_e32 v18, v190
	v_mov_b32_e32 v19, v191
	v_mov_b32_e32 v22, v17
	v_mov_b32_e32 v23, v18
	v_mov_b32_e32 v17, v19
	v_pk_add_f32 v[16:17], v[22:23], v[16:17]
	s_nop 0
	v_add_f32_e32 v16, v16, v17
	v_fmamk_f32 v16, v16, 0x3a800000, v207
	v_rsq_f32_e32 v16, v16
	s_nop 0
	v_pk_mul_f32 v[12:13], v[12:13], v[16:17] op_sel_hi:[1,0]
	v_pk_mul_f32 v[18:19], v[10:11], v[16:17] op_sel_hi:[1,0]
	v_pk_mul_f32 v[10:11], v[8:9], v[16:17] op_sel_hi:[1,0]
	v_cvt_pk_bf16_f32 v8, v12, v13
	v_lshl_add_u64 v[12:13], s[20:21], 0, v[20:21]
	v_lshlrev_b64 v[12:13], 7, v[12:13]
	v_pk_mul_f32 v[14:15], v[14:15], v[16:17] op_sel_hi:[1,0]
	v_lshl_add_u64 v[12:13], v[136:137], 0, v[12:13]
	v_cvt_pk_bf16_f32 v9, v14, v15
	v_pk_mul_f32 v[4:5], v[4:5], v[16:17] op_sel_hi:[1,0]
	v_cvt_pk_bf16_f32 v10, v10, v11
	v_cvt_pk_bf16_f32 v11, v18, v19
	global_store_dwordx4 v[12:13], v[8:11], off
	v_pk_mul_f32 v[6:7], v[6:7], v[16:17] op_sel_hi:[1,0]
	s_nop 0
	v_pk_mul_f32 v[8:9], v[2:3], v[16:17] op_sel_hi:[1,0]
	v_pk_mul_f32 v[2:3], v[0:1], v[16:17] op_sel_hi:[1,0]
	v_cvt_pk_bf16_f32 v0, v4, v5
	v_lshl_add_u64 v[4:5], s[22:23], 0, v[20:21]
	v_lshlrev_b64 v[4:5], 7, v[4:5]
	v_lshl_add_u64 v[4:5], v[136:137], 0, v[4:5]
	v_cvt_pk_bf16_f32 v1, v6, v7
	v_cvt_pk_bf16_f32 v2, v2, v3
	v_cvt_pk_bf16_f32 v3, v8, v9
	global_store_dwordx4 v[4:5], v[0:3], off
	s_cbranch_vccnz .LBB0_764
	s_andn2_b64 vcc, exec, s[6:7]
	s_cbranch_vccnz .LBB0_763
	s_barrier
	s_branch .LBB0_763
